# ml_out_tile: K/V staging loads batched up-front + S stage rewritten (batched LDS reads, select masks instead of 32 exec-masked blocks); math unchanged
# speedup vs baseline: 1.0228x; 1.0102x over previous
; __device__ __forceinline__ bf16_t f2bf(float f) { return (bf16_t)(pack2(f, 0.f) & 0xffffu); }
; __device__ __forceinline__ float siluf(float x) { return x * frcp(1.f + fexp(-x)); }
; __device__ __forceinline__ void ml_conv8_comp(const uint4* u, const float* wc, int ccol, int L, int pos, float* o) {
; #pragma unroll
;   for (int e = 0; e < 8; ++e) o[e] = 0.f;
; #pragma unroll
;   for (int j = 0; j < 4; ++j) {
;     const int pp = pos + j - 1;
;     const float mk = (pp >= 0 && pp < L) ? 1.f : 0.f;
;     float f[8];
;     unpack8(u[j], f);
;     const float4 w0 = *(const float4*)(wc + j * 1024 + ccol);
;     const float4 w1 = *(const float4*)(wc + j * 1024 + ccol + 4);
;     o[0] += f[0] * (w0.x * mk); o[1] += f[1] * (w0.y * mk); o[2] += f[2] * (w0.z * mk); o[3] += f[3] * (w0.w * mk);
;     o[4] += f[4] * (w1.x * mk); o[5] += f[5] * (w1.y * mk); o[6] += f[6] * (w1.z * mk); o[7] += f[7] * (w1.w * mk);
;   }
; #pragma unroll
;   for (int e = 0; e < 8; ++e) o[e] = siluf(o[e]);
; }
; __device__ void ml_out_tile(unsigned char* lds, const Params& p, int l, int b, int h, int n) {
;     ...
;   {
;     const int s = tid & 127, ec0 = tid >> 7;
;     const int row = ml_row_pos(b, isctx, p0 + s);
; #pragma unroll 2
;     for (int i = 0; i < 4; ++i) {
;       const int ec = ec0 + 4 * i;
;       float k8[8], v8[8];
;       ml_conv8(z, wc, 768 + 512 + h * 128 + ec * 8, 512 + h * 128 + ec * 8, b, isctx, L, p0 + s, k8);
; #pragma unroll
;       for (int e = 0; e < 8; ++e) k8[e] *= 0.08838834764831845f;
;       *(uint4*)(Ks + s * 136 + ec * 8) = pack8(k8);
;       const uint4 vu = *(const uint4*)(z + (size_t)row * ZS + 768 + 1024 + h * 128 + ec * 8);
;       unpack8(vu, v8);
; #pragma unroll
;       for (int e = 0; e < 8; ++e) VT[(ec * 8 + e) * 136 + s] = f2bf(v8[e]);
;     }
;   }
.LBB0_730:
	v_ashrrev_i32_e32 v5, 31, v4
	v_lshl_add_u64 v[174:175], s[96:97], 0, v[4:5]
	v_lshl_add_u64 v[176:177], v[174:175], 1, s[88:89]
	v_lshl_add_u64 v[178:179], v[176:177], 0, v[16:17]
	v_lshl_add_u64 v[180:181], v[176:177], 0, v[18:19]
	v_lshl_add_u64 v[182:183], v[176:177], 0, v[20:21]
	v_lshl_add_u64 v[184:185], v[176:177], 0, v[22:23]
	v_lshl_add_u64 v[186:187], v[4:5], 1, v[14:15]
	v_lshlrev_b32_e32 v188, 2, v174
	v_add_u32_e32 v188, 0x800, v188
	v_add_u32_e32 v189, 0x1000, v188
	v_add_u32_e32 v190, 0x2000, v188
	v_add_u32_e32 v191, 0x3000, v188
	v_add_u32_e32 v200, 0x11000, v28
	global_load_dwordx4 v[30:33], v[178:179], off offset:2560
	global_load_dwordx4 v[34:37], v[180:181], off offset:2560
	global_load_dwordx4 v[38:41], v[182:183], off offset:2560
	global_load_dwordx4 v[42:45], v[184:185], off offset:2560
	global_load_dwordx4 v[110:113], v188, s[14:15] offset:0
	global_load_dwordx4 v[114:117], v188, s[14:15] offset:16
	global_load_dwordx4 v[118:121], v189, s[14:15] offset:0
	global_load_dwordx4 v[122:125], v189, s[14:15] offset:16
	global_load_dwordx4 v[126:129], v190, s[14:15] offset:0
	global_load_dwordx4 v[130:133], v190, s[14:15] offset:16
	global_load_dwordx4 v[134:137], v191, s[14:15] offset:0
	global_load_dwordx4 v[138:141], v191, s[14:15] offset:16
	global_load_dwordx4 v[46:49], v[178:179], off offset:2624
	global_load_dwordx4 v[50:53], v[180:181], off offset:2624
	global_load_dwordx4 v[54:57], v[182:183], off offset:2624
	global_load_dwordx4 v[58:61], v[184:185], off offset:2624
	global_load_dwordx4 v[142:145], v188, s[14:15] offset:128
	global_load_dwordx4 v[146:149], v188, s[14:15] offset:144
	global_load_dwordx4 v[150:153], v189, s[14:15] offset:128
	global_load_dwordx4 v[154:157], v189, s[14:15] offset:144
	global_load_dwordx4 v[158:161], v190, s[14:15] offset:128
	global_load_dwordx4 v[162:165], v190, s[14:15] offset:144
	global_load_dwordx4 v[166:169], v191, s[14:15] offset:128
	global_load_dwordx4 v[170:173], v191, s[14:15] offset:144
	global_load_dwordx4 v[62:65], v[178:179], off offset:2688
	global_load_dwordx4 v[66:69], v[180:181], off offset:2688
	global_load_dwordx4 v[70:73], v[182:183], off offset:2688
	global_load_dwordx4 v[74:77], v[184:185], off offset:2688
	global_load_dwordx4 v[78:81], v[178:179], off offset:2752
	global_load_dwordx4 v[82:85], v[180:181], off offset:2752
	global_load_dwordx4 v[86:89], v[182:183], off offset:2752
	global_load_dwordx4 v[90:93], v[184:185], off offset:2752
	global_load_dwordx4 v[94:97], v[186:187], off offset:3584
	global_load_dwordx4 v[98:101], v[186:187], off offset:3648
	global_load_dwordx4 v[102:105], v[186:187], off offset:3712
	global_load_dwordx4 v[106:109], v[186:187], off offset:3776
	s_waitcnt vmcnt(24)
	v_lshlrev_b32_e32 v0, 16, v30
	v_and_b32_e32 v1, 0xffff0000, v30
	v_pk_mul_f32 v[212:213], v[6:7], v[110:111]
	v_lshlrev_b32_e32 v2, 16, v31
	v_and_b32_e32 v3, 0xffff0000, v31
	v_pk_mul_f32 v[214:215], v[6:7], v[112:113]
	v_lshlrev_b32_e32 v230, 16, v32
	v_and_b32_e32 v231, 0xffff0000, v32
	v_pk_mul_f32 v[216:217], v[6:7], v[114:115]
	v_lshlrev_b32_e32 v232, 16, v33
	v_and_b32_e32 v233, 0xffff0000, v33
	v_pk_mul_f32 v[218:219], v[6:7], v[116:117]
	v_pk_fma_f32 v[204:205], v[212:213], v[0:1], 0 op_sel_hi:[1,1,0]
	v_pk_fma_f32 v[206:207], v[214:215], v[2:3], 0 op_sel_hi:[1,1,0]
	v_pk_fma_f32 v[208:209], v[216:217], v[230:231], 0 op_sel_hi:[1,1,0]
	v_pk_fma_f32 v[210:211], v[218:219], v[232:233], 0 op_sel_hi:[1,1,0]
	v_lshlrev_b32_e32 v0, 16, v34
	v_and_b32_e32 v1, 0xffff0000, v34
	v_pk_mul_f32 v[212:213], v[8:9], v[118:119]
	v_lshlrev_b32_e32 v2, 16, v35
	v_and_b32_e32 v3, 0xffff0000, v35
	v_pk_mul_f32 v[214:215], v[8:9], v[120:121]
	v_lshlrev_b32_e32 v230, 16, v36
	v_and_b32_e32 v231, 0xffff0000, v36
	v_pk_mul_f32 v[216:217], v[8:9], v[122:123]
	v_lshlrev_b32_e32 v232, 16, v37
	v_and_b32_e32 v233, 0xffff0000, v37
	v_pk_mul_f32 v[218:219], v[8:9], v[124:125]
	v_pk_fma_f32 v[204:205], v[212:213], v[0:1], v[204:205]
	v_pk_fma_f32 v[206:207], v[214:215], v[2:3], v[206:207]
	v_pk_fma_f32 v[208:209], v[216:217], v[230:231], v[208:209]
	v_pk_fma_f32 v[210:211], v[218:219], v[232:233], v[210:211]
	v_lshlrev_b32_e32 v0, 16, v38
	v_and_b32_e32 v1, 0xffff0000, v38
	v_pk_mul_f32 v[212:213], v[10:11], v[126:127]
	v_lshlrev_b32_e32 v2, 16, v39
	v_and_b32_e32 v3, 0xffff0000, v39
	v_pk_mul_f32 v[214:215], v[10:11], v[128:129]
	v_lshlrev_b32_e32 v230, 16, v40
	v_and_b32_e32 v231, 0xffff0000, v40
	v_pk_mul_f32 v[216:217], v[10:11], v[130:131]
	v_lshlrev_b32_e32 v232, 16, v41
	v_and_b32_e32 v233, 0xffff0000, v41
	v_pk_mul_f32 v[218:219], v[10:11], v[132:133]
	v_pk_fma_f32 v[204:205], v[212:213], v[0:1], v[204:205]
	v_pk_fma_f32 v[206:207], v[214:215], v[2:3], v[206:207]
	v_pk_fma_f32 v[208:209], v[216:217], v[230:231], v[208:209]
	v_pk_fma_f32 v[210:211], v[218:219], v[232:233], v[210:211]
	v_lshlrev_b32_e32 v0, 16, v42
	v_and_b32_e32 v1, 0xffff0000, v42
	v_pk_mul_f32 v[212:213], v[12:13], v[134:135]
	v_lshlrev_b32_e32 v2, 16, v43
	v_and_b32_e32 v3, 0xffff0000, v43
	v_pk_mul_f32 v[214:215], v[12:13], v[136:137]
	v_lshlrev_b32_e32 v230, 16, v44
	v_and_b32_e32 v231, 0xffff0000, v44
	v_pk_mul_f32 v[216:217], v[12:13], v[138:139]
	v_lshlrev_b32_e32 v232, 16, v45
	v_and_b32_e32 v233, 0xffff0000, v45
	v_pk_mul_f32 v[218:219], v[12:13], v[140:141]
	v_pk_fma_f32 v[204:205], v[212:213], v[0:1], v[204:205]
	v_pk_fma_f32 v[206:207], v[214:215], v[2:3], v[206:207]
	v_pk_fma_f32 v[208:209], v[216:217], v[230:231], v[208:209]
	v_pk_fma_f32 v[210:211], v[218:219], v[232:233], v[210:211]
	v_mul_f32_e32 v212, 0xbfb8aa3b, v204
	v_mul_f32_e32 v213, 0xbfb8aa3b, v205
	v_mul_f32_e32 v214, 0xbfb8aa3b, v206
; __device__ __forceinline__ bf16_t f2bf(float f) { return (bf16_t)(pack2(f, 0.f) & 0xffffu); }
; __device__ __forceinline__ float siluf(float x) { return x * frcp(1.f + fexp(-x)); }
; __device__ __forceinline__ void ml_conv8_comp(const uint4* u, const float* wc, int ccol, int L, int pos, float* o) {
; #pragma unroll
;   for (int e = 0; e < 8; ++e) o[e] = 0.f;
; #pragma unroll
;   for (int j = 0; j < 4; ++j) {
;     const int pp = pos + j - 1;
;     const float mk = (pp >= 0 && pp < L) ? 1.f : 0.f;
;     float f[8];
;     unpack8(u[j], f);
;     const float4 w0 = *(const float4*)(wc + j * 1024 + ccol);
;     const float4 w1 = *(const float4*)(wc + j * 1024 + ccol + 4);
;     o[0] += f[0] * (w0.x * mk); o[1] += f[1] * (w0.y * mk); o[2] += f[2] * (w0.z * mk); o[3] += f[3] * (w0.w * mk);
;     o[4] += f[4] * (w1.x * mk); o[5] += f[5] * (w1.y * mk); o[6] += f[6] * (w1.z * mk); o[7] += f[7] * (w1.w * mk);
;   }
; #pragma unroll
;   for (int e = 0; e < 8; ++e) o[e] = siluf(o[e]);
; }
; __device__ void ml_out_tile(unsigned char* lds, const Params& p, int l, int b, int h, int n) {
;     ...
;   {
;     const int s = tid & 127, ec0 = tid >> 7;
;     const int row = ml_row_pos(b, isctx, p0 + s);
; #pragma unroll 2
;     for (int i = 0; i < 4; ++i) {
;       const int ec = ec0 + 4 * i;
;       float k8[8], v8[8];
;       ml_conv8(z, wc, 768 + 512 + h * 128 + ec * 8, 512 + h * 128 + ec * 8, b, isctx, L, p0 + s, k8);
; #pragma unroll
;       for (int e = 0; e < 8; ++e) k8[e] *= 0.08838834764831845f;
;       *(uint4*)(Ks + s * 136 + ec * 8) = pack8(k8);
;       const uint4 vu = *(const uint4*)(z + (size_t)row * ZS + 768 + 1024 + h * 128 + ec * 8);
;       unpack8(vu, v8);
; #pragma unroll
;       for (int e = 0; e < 8; ++e) VT[(ec * 8 + e) * 136 + s] = f2bf(v8[e]);
;     }
;   }
	v_mul_f32_e32 v215, 0xbfb8aa3b, v207
	v_mul_f32_e32 v216, 0xbfb8aa3b, v208
	v_mul_f32_e32 v217, 0xbfb8aa3b, v209
	v_mul_f32_e32 v218, 0xbfb8aa3b, v210
	v_mul_f32_e32 v219, 0xbfb8aa3b, v211
	v_exp_f32_e32 v212, v212
	v_exp_f32_e32 v213, v213
	v_exp_f32_e32 v214, v214
	v_exp_f32_e32 v215, v215
	v_exp_f32_e32 v216, v216
	v_exp_f32_e32 v217, v217
	v_exp_f32_e32 v218, v218
	v_exp_f32_e32 v219, v219
	v_add_f32_e32 v212, 1.0, v212
	v_add_f32_e32 v213, 1.0, v213
	v_add_f32_e32 v214, 1.0, v214
	v_add_f32_e32 v215, 1.0, v215
	v_add_f32_e32 v216, 1.0, v216
	v_add_f32_e32 v217, 1.0, v217
	v_add_f32_e32 v218, 1.0, v218
	v_add_f32_e32 v219, 1.0, v219
	v_rcp_f32_e32 v212, v212
	v_rcp_f32_e32 v213, v213
	v_rcp_f32_e32 v214, v214
	v_rcp_f32_e32 v215, v215
	v_rcp_f32_e32 v216, v216
	v_rcp_f32_e32 v217, v217
	v_rcp_f32_e32 v218, v218
	v_rcp_f32_e32 v219, v219
	s_nop 0
	v_pk_mul_f32 v[204:205], v[204:205], v[212:213]
	v_pk_mul_f32 v[206:207], v[206:207], v[214:215]
	v_pk_mul_f32 v[208:209], v[208:209], v[216:217]
	v_pk_mul_f32 v[210:211], v[210:211], v[218:219]
	v_pk_mul_f32 v[204:205], v[204:205], s[6:7] op_sel_hi:[1,0]
	v_pk_mul_f32 v[206:207], v[206:207], s[6:7] op_sel_hi:[1,0]
	v_pk_mul_f32 v[208:209], v[208:209], s[6:7] op_sel_hi:[1,0]
	v_pk_mul_f32 v[210:211], v[210:211], s[6:7] op_sel_hi:[1,0]
	v_cvt_pk_bf16_f32 v234, v204, v205
	v_cvt_pk_bf16_f32 v235, v206, v207
	v_cvt_pk_bf16_f32 v236, v208, v209
	v_cvt_pk_bf16_f32 v237, v210, v211
	ds_write_b128 v29, v[234:237]
	global_load_dwordx4 v[110:113], v188, s[14:15] offset:256
	global_load_dwordx4 v[114:117], v188, s[14:15] offset:272
	global_load_dwordx4 v[118:121], v189, s[14:15] offset:256
	global_load_dwordx4 v[122:125], v189, s[14:15] offset:272
	global_load_dwordx4 v[126:129], v190, s[14:15] offset:256
	global_load_dwordx4 v[130:133], v190, s[14:15] offset:272
	global_load_dwordx4 v[134:137], v191, s[14:15] offset:256
	global_load_dwordx4 v[138:141], v191, s[14:15] offset:272
	s_waitcnt vmcnt(20)
	v_lshlrev_b32_e32 v0, 16, v46
	v_and_b32_e32 v1, 0xffff0000, v46
	v_pk_mul_f32 v[212:213], v[6:7], v[142:143]
	v_lshlrev_b32_e32 v2, 16, v47
	v_and_b32_e32 v3, 0xffff0000, v47
	v_pk_mul_f32 v[214:215], v[6:7], v[144:145]
	v_lshlrev_b32_e32 v230, 16, v48
	v_and_b32_e32 v231, 0xffff0000, v48
	v_pk_mul_f32 v[216:217], v[6:7], v[146:147]
	v_lshlrev_b32_e32 v232, 16, v49
	v_and_b32_e32 v233, 0xffff0000, v49
	v_pk_mul_f32 v[218:219], v[6:7], v[148:149]
	v_pk_fma_f32 v[204:205], v[212:213], v[0:1], 0 op_sel_hi:[1,1,0]
	v_pk_fma_f32 v[206:207], v[214:215], v[2:3], 0 op_sel_hi:[1,1,0]
	v_pk_fma_f32 v[208:209], v[216:217], v[230:231], 0 op_sel_hi:[1,1,0]
	v_pk_fma_f32 v[210:211], v[218:219], v[232:233], 0 op_sel_hi:[1,1,0]
	v_lshlrev_b32_e32 v0, 16, v50
	v_and_b32_e32 v1, 0xffff0000, v50
	v_pk_mul_f32 v[212:213], v[8:9], v[150:151]
	v_lshlrev_b32_e32 v2, 16, v51
	v_and_b32_e32 v3, 0xffff0000, v51
	v_pk_mul_f32 v[214:215], v[8:9], v[152:153]
	v_lshlrev_b32_e32 v230, 16, v52
	v_and_b32_e32 v231, 0xffff0000, v52
	v_pk_mul_f32 v[216:217], v[8:9], v[154:155]
	v_lshlrev_b32_e32 v232, 16, v53
	v_and_b32_e32 v233, 0xffff0000, v53
	v_pk_mul_f32 v[218:219], v[8:9], v[156:157]
	v_pk_fma_f32 v[204:205], v[212:213], v[0:1], v[204:205]
	v_pk_fma_f32 v[206:207], v[214:215], v[2:3], v[206:207]
	v_pk_fma_f32 v[208:209], v[216:217], v[230:231], v[208:209]
	v_pk_fma_f32 v[210:211], v[218:219], v[232:233], v[210:211]
	v_lshlrev_b32_e32 v0, 16, v54
	v_and_b32_e32 v1, 0xffff0000, v54
	v_pk_mul_f32 v[212:213], v[10:11], v[158:159]
	v_lshlrev_b32_e32 v2, 16, v55
	v_and_b32_e32 v3, 0xffff0000, v55
	v_pk_mul_f32 v[214:215], v[10:11], v[160:161]
	v_lshlrev_b32_e32 v230, 16, v56
	v_and_b32_e32 v231, 0xffff0000, v56
	v_pk_mul_f32 v[216:217], v[10:11], v[162:163]
	v_lshlrev_b32_e32 v232, 16, v57
	v_and_b32_e32 v233, 0xffff0000, v57
	v_pk_mul_f32 v[218:219], v[10:11], v[164:165]
	v_pk_fma_f32 v[204:205], v[212:213], v[0:1], v[204:205]
	v_pk_fma_f32 v[206:207], v[214:215], v[2:3], v[206:207]
	v_pk_fma_f32 v[208:209], v[216:217], v[230:231], v[208:209]
	v_pk_fma_f32 v[210:211], v[218:219], v[232:233], v[210:211]
	v_lshlrev_b32_e32 v0, 16, v58
	v_and_b32_e32 v1, 0xffff0000, v58
	v_pk_mul_f32 v[212:213], v[12:13], v[166:167]
	v_lshlrev_b32_e32 v2, 16, v59
	v_and_b32_e32 v3, 0xffff0000, v59
	v_pk_mul_f32 v[214:215], v[12:13], v[168:169]
	v_lshlrev_b32_e32 v230, 16, v60
	v_and_b32_e32 v231, 0xffff0000, v60
	v_pk_mul_f32 v[216:217], v[12:13], v[170:171]
	v_lshlrev_b32_e32 v232, 16, v61
	v_and_b32_e32 v233, 0xffff0000, v61
	v_pk_mul_f32 v[218:219], v[12:13], v[172:173]
	v_pk_fma_f32 v[204:205], v[212:213], v[0:1], v[204:205]
	v_pk_fma_f32 v[206:207], v[214:215], v[2:3], v[206:207]
	v_pk_fma_f32 v[208:209], v[216:217], v[230:231], v[208:209]
	v_pk_fma_f32 v[210:211], v[218:219], v[232:233], v[210:211]
	v_mul_f32_e32 v212, 0xbfb8aa3b, v204
	v_mul_f32_e32 v213, 0xbfb8aa3b, v205
	v_mul_f32_e32 v214, 0xbfb8aa3b, v206
	v_mul_f32_e32 v215, 0xbfb8aa3b, v207
	v_mul_f32_e32 v216, 0xbfb8aa3b, v208
	v_mul_f32_e32 v217, 0xbfb8aa3b, v209
	v_mul_f32_e32 v218, 0xbfb8aa3b, v210
	v_mul_f32_e32 v219, 0xbfb8aa3b, v211
	v_exp_f32_e32 v212, v212
	v_exp_f32_e32 v213, v213
	v_exp_f32_e32 v214, v214
	v_exp_f32_e32 v215, v215
	v_exp_f32_e32 v216, v216
	v_exp_f32_e32 v217, v217
	v_exp_f32_e32 v218, v218
	v_exp_f32_e32 v219, v219
	v_add_f32_e32 v212, 1.0, v212
	v_add_f32_e32 v213, 1.0, v213
	v_add_f32_e32 v214, 1.0, v214
	v_add_f32_e32 v215, 1.0, v215
	v_add_f32_e32 v216, 1.0, v216
	v_add_f32_e32 v217, 1.0, v217
	v_add_f32_e32 v218, 1.0, v218
	v_add_f32_e32 v219, 1.0, v219
	v_rcp_f32_e32 v212, v212
	v_rcp_f32_e32 v213, v213
	v_rcp_f32_e32 v214, v214
	v_rcp_f32_e32 v215, v215
	v_rcp_f32_e32 v216, v216
	v_rcp_f32_e32 v217, v217
	v_rcp_f32_e32 v218, v218
	v_rcp_f32_e32 v219, v219
	s_nop 0
	v_pk_mul_f32 v[204:205], v[204:205], v[212:213]
	v_pk_mul_f32 v[206:207], v[206:207], v[214:215]
	v_pk_mul_f32 v[208:209], v[208:209], v[216:217]
	v_pk_mul_f32 v[210:211], v[210:211], v[218:219]
	v_pk_mul_f32 v[204:205], v[204:205], s[6:7] op_sel_hi:[1,0]
	v_pk_mul_f32 v[206:207], v[206:207], s[6:7] op_sel_hi:[1,0]
	v_pk_mul_f32 v[208:209], v[208:209], s[6:7] op_sel_hi:[1,0]
	v_pk_mul_f32 v[210:211], v[210:211], s[6:7] op_sel_hi:[1,0]
	v_cvt_pk_bf16_f32 v234, v204, v205
	v_cvt_pk_bf16_f32 v235, v206, v207
	v_cvt_pk_bf16_f32 v236, v208, v209
	v_cvt_pk_bf16_f32 v237, v210, v211
	ds_write_b128 v29, v[234:237] offset:64
	global_load_dwordx4 v[142:145], v188, s[14:15] offset:384
	global_load_dwordx4 v[146:149], v188, s[14:15] offset:400
	global_load_dwordx4 v[150:153], v189, s[14:15] offset:384
	global_load_dwordx4 v[154:157], v189, s[14:15] offset:400
	global_load_dwordx4 v[158:161], v190, s[14:15] offset:384
	global_load_dwordx4 v[162:165], v190, s[14:15] offset:400
	global_load_dwordx4 v[166:169], v191, s[14:15] offset:384
	global_load_dwordx4 v[170:173], v191, s[14:15] offset:400
	s_waitcnt vmcnt(8)
; __device__ __forceinline__ bf16_t f2bf(float f) { return (bf16_t)(pack2(f, 0.f) & 0xffffu); }
; __device__ void ml_out_tile(unsigned char* lds, const Params& p, int l, int b, int h, int n) {
;     ...
;   {
;     const int s = tid & 127, ec0 = tid >> 7;
;     const int row = ml_row_pos(b, isctx, p0 + s);
; #pragma unroll 2
;     for (int i = 0; i < 4; ++i) {
;       const int ec = ec0 + 4 * i;
;       float k8[8], v8[8];
;       ml_conv8(z, wc, 768 + 512 + h * 128 + ec * 8, 512 + h * 128 + ec * 8, b, isctx, L, p0 + s, k8);
; #pragma unroll
;       for (int e = 0; e < 8; ++e) k8[e] *= 0.08838834764831845f;
;       *(uint4*)(Ks + s * 136 + ec * 8) = pack8(k8);
;       const uint4 vu = *(const uint4*)(z + (size_t)row * ZS + 768 + 1024 + h * 128 + ec * 8);
;       unpack8(vu, v8);
; #pragma unroll
;       for (int e = 0; e < 8; ++e) VT[(ec * 8 + e) * 136 + s] = f2bf(v8[e]);
;     }
;   }
	v_lshlrev_b32_e32 v0, 16, v62
	v_and_b32_e32 v1, 0xffff0000, v62
	v_pk_mul_f32 v[212:213], v[6:7], v[110:111]
	v_lshlrev_b32_e32 v2, 16, v63
	v_and_b32_e32 v3, 0xffff0000, v63
	v_pk_mul_f32 v[214:215], v[6:7], v[112:113]
	v_lshlrev_b32_e32 v230, 16, v64
	v_and_b32_e32 v231, 0xffff0000, v64
	v_pk_mul_f32 v[216:217], v[6:7], v[114:115]
	v_lshlrev_b32_e32 v232, 16, v65
	v_and_b32_e32 v233, 0xffff0000, v65
	v_pk_mul_f32 v[218:219], v[6:7], v[116:117]
	v_pk_fma_f32 v[204:205], v[212:213], v[0:1], 0 op_sel_hi:[1,1,0]
	v_pk_fma_f32 v[206:207], v[214:215], v[2:3], 0 op_sel_hi:[1,1,0]
	v_pk_fma_f32 v[208:209], v[216:217], v[230:231], 0 op_sel_hi:[1,1,0]
	v_pk_fma_f32 v[210:211], v[218:219], v[232:233], 0 op_sel_hi:[1,1,0]
	v_lshlrev_b32_e32 v0, 16, v66
	v_and_b32_e32 v1, 0xffff0000, v66
	v_pk_mul_f32 v[212:213], v[8:9], v[118:119]
	v_lshlrev_b32_e32 v2, 16, v67
	v_and_b32_e32 v3, 0xffff0000, v67
	v_pk_mul_f32 v[214:215], v[8:9], v[120:121]
	v_lshlrev_b32_e32 v230, 16, v68
	v_and_b32_e32 v231, 0xffff0000, v68
	v_pk_mul_f32 v[216:217], v[8:9], v[122:123]
	v_lshlrev_b32_e32 v232, 16, v69
	v_and_b32_e32 v233, 0xffff0000, v69
	v_pk_mul_f32 v[218:219], v[8:9], v[124:125]
	v_pk_fma_f32 v[204:205], v[212:213], v[0:1], v[204:205]
	v_pk_fma_f32 v[206:207], v[214:215], v[2:3], v[206:207]
	v_pk_fma_f32 v[208:209], v[216:217], v[230:231], v[208:209]
	v_pk_fma_f32 v[210:211], v[218:219], v[232:233], v[210:211]
	v_lshlrev_b32_e32 v0, 16, v70
	v_and_b32_e32 v1, 0xffff0000, v70
	v_pk_mul_f32 v[212:213], v[10:11], v[126:127]
	v_lshlrev_b32_e32 v2, 16, v71
	v_and_b32_e32 v3, 0xffff0000, v71
	v_pk_mul_f32 v[214:215], v[10:11], v[128:129]
	v_lshlrev_b32_e32 v230, 16, v72
	v_and_b32_e32 v231, 0xffff0000, v72
	v_pk_mul_f32 v[216:217], v[10:11], v[130:131]
	v_lshlrev_b32_e32 v232, 16, v73
	v_and_b32_e32 v233, 0xffff0000, v73
	v_pk_mul_f32 v[218:219], v[10:11], v[132:133]
	v_pk_fma_f32 v[204:205], v[212:213], v[0:1], v[204:205]
	v_pk_fma_f32 v[206:207], v[214:215], v[2:3], v[206:207]
	v_pk_fma_f32 v[208:209], v[216:217], v[230:231], v[208:209]
	v_pk_fma_f32 v[210:211], v[218:219], v[232:233], v[210:211]
	v_lshlrev_b32_e32 v0, 16, v74
	v_and_b32_e32 v1, 0xffff0000, v74
	v_pk_mul_f32 v[212:213], v[12:13], v[134:135]
	v_lshlrev_b32_e32 v2, 16, v75
	v_and_b32_e32 v3, 0xffff0000, v75
	v_pk_mul_f32 v[214:215], v[12:13], v[136:137]
	v_lshlrev_b32_e32 v230, 16, v76
	v_and_b32_e32 v231, 0xffff0000, v76
	v_pk_mul_f32 v[216:217], v[12:13], v[138:139]
	v_lshlrev_b32_e32 v232, 16, v77
	v_and_b32_e32 v233, 0xffff0000, v77
	v_pk_mul_f32 v[218:219], v[12:13], v[140:141]
	v_pk_fma_f32 v[204:205], v[212:213], v[0:1], v[204:205]
	v_pk_fma_f32 v[206:207], v[214:215], v[2:3], v[206:207]
	v_pk_fma_f32 v[208:209], v[216:217], v[230:231], v[208:209]
	v_pk_fma_f32 v[210:211], v[218:219], v[232:233], v[210:211]
	v_mul_f32_e32 v212, 0xbfb8aa3b, v204
	v_mul_f32_e32 v213, 0xbfb8aa3b, v205
	v_mul_f32_e32 v214, 0xbfb8aa3b, v206
	v_mul_f32_e32 v215, 0xbfb8aa3b, v207
	v_mul_f32_e32 v216, 0xbfb8aa3b, v208
	v_mul_f32_e32 v217, 0xbfb8aa3b, v209
	v_mul_f32_e32 v218, 0xbfb8aa3b, v210
	v_mul_f32_e32 v219, 0xbfb8aa3b, v211
	v_exp_f32_e32 v212, v212
	v_exp_f32_e32 v213, v213
	v_exp_f32_e32 v214, v214
	v_exp_f32_e32 v215, v215
	v_exp_f32_e32 v216, v216
	v_exp_f32_e32 v217, v217
	v_exp_f32_e32 v218, v218
	v_exp_f32_e32 v219, v219
	v_add_f32_e32 v212, 1.0, v212
	v_add_f32_e32 v213, 1.0, v213
	v_add_f32_e32 v214, 1.0, v214
	v_add_f32_e32 v215, 1.0, v215
	v_add_f32_e32 v216, 1.0, v216
	v_add_f32_e32 v217, 1.0, v217
	v_add_f32_e32 v218, 1.0, v218
	v_add_f32_e32 v219, 1.0, v219
	v_rcp_f32_e32 v212, v212
	v_rcp_f32_e32 v213, v213
	v_rcp_f32_e32 v214, v214
	v_rcp_f32_e32 v215, v215
	v_rcp_f32_e32 v216, v216
	v_rcp_f32_e32 v217, v217
	v_rcp_f32_e32 v218, v218
	v_rcp_f32_e32 v219, v219
	s_nop 0
	v_pk_mul_f32 v[204:205], v[204:205], v[212:213]
	v_pk_mul_f32 v[206:207], v[206:207], v[214:215]
	v_pk_mul_f32 v[208:209], v[208:209], v[216:217]
	v_pk_mul_f32 v[210:211], v[210:211], v[218:219]
	v_pk_mul_f32 v[204:205], v[204:205], s[6:7] op_sel_hi:[1,0]
	v_pk_mul_f32 v[206:207], v[206:207], s[6:7] op_sel_hi:[1,0]
	v_pk_mul_f32 v[208:209], v[208:209], s[6:7] op_sel_hi:[1,0]
	v_pk_mul_f32 v[210:211], v[210:211], s[6:7] op_sel_hi:[1,0]
	v_cvt_pk_bf16_f32 v234, v204, v205
	v_cvt_pk_bf16_f32 v235, v206, v207
	v_cvt_pk_bf16_f32 v236, v208, v209
	v_cvt_pk_bf16_f32 v237, v210, v211
	ds_write_b128 v29, v[234:237] offset:128
	ds_write_b16 v200, v94
	ds_write_b16_d16_hi v200, v94 offset:272
	ds_write_b16 v200, v95 offset:544
	ds_write_b16_d16_hi v200, v95 offset:816
	ds_write_b16 v200, v96 offset:1088
	ds_write_b16_d16_hi v200, v96 offset:1360
	ds_write_b16 v200, v97 offset:1632
	ds_write_b16_d16_hi v200, v97 offset:1904
	ds_write_b16 v200, v98 offset:8704
	ds_write_b16_d16_hi v200, v98 offset:8976
	ds_write_b16 v200, v99 offset:9248
	ds_write_b16_d16_hi v200, v99 offset:9520
	ds_write_b16 v200, v100 offset:9792
	ds_write_b16_d16_hi v200, v100 offset:10064
	ds_write_b16 v200, v101 offset:10336
	ds_write_b16_d16_hi v200, v101 offset:10608
	ds_write_b16 v200, v102 offset:17408
	ds_write_b16_d16_hi v200, v102 offset:17680
	ds_write_b16 v200, v103 offset:17952
	ds_write_b16_d16_hi v200, v103 offset:18224
	ds_write_b16 v200, v104 offset:18496
	ds_write_b16_d16_hi v200, v104 offset:18768
	ds_write_b16 v200, v105 offset:19040
	ds_write_b16_d16_hi v200, v105 offset:19312
	ds_write_b16 v200, v106 offset:26112
	ds_write_b16_d16_hi v200, v106 offset:26384
	ds_write_b16 v200, v107 offset:26656
	ds_write_b16_d16_hi v200, v107 offset:26928
	ds_write_b16 v200, v108 offset:27200
	ds_write_b16_d16_hi v200, v108 offset:27472
	ds_write_b16 v200, v109 offset:27744
	ds_write_b16_d16_hi v200, v109 offset:28016
	s_waitcnt vmcnt(0)
; __device__ __forceinline__ bf16_t f2bf(float f) { return (bf16_t)(pack2(f, 0.f) & 0xffffu); }
; __device__ __forceinline__ int sidx(int dir, int b, int h, int n) { return ((dir * 8 + b) * 4 + h) * 18 + n; }
; __device__ void ml_out_tile(unsigned char* lds, const Params& p, int l, int b, int h, int n) {
;     ...
;   {
;     const int s = tid & 127, ec0 = tid >> 7;
;     const int row = ml_row_pos(b, isctx, p0 + s);
; #pragma unroll 2
;     for (int i = 0; i < 4; ++i) {
;       const int ec = ec0 + 4 * i;
;       float k8[8], v8[8];
;       ml_conv8(z, wc, 768 + 512 + h * 128 + ec * 8, 512 + h * 128 + ec * 8, b, isctx, L, p0 + s, k8);
; #pragma unroll
;       for (int e = 0; e < 8; ++e) k8[e] *= 0.08838834764831845f;
;       *(uint4*)(Ks + s * 136 + ec * 8) = pack8(k8);
;       const uint4 vu = *(const uint4*)(z + (size_t)row * ZS + 768 + 1024 + h * 128 + ec * 8);
;       unpack8(vu, v8);
; #pragma unroll
;       for (int e = 0; e < 8; ++e) VT[(ec * 8 + e) * 136 + s] = f2bf(v8[e]);
;     }
;   }
;   uint4 c0f[4];
;   {
;     const bf16_t* Cf = Cst + (size_t)sidx(0, b, h, n) * 16384;
; #pragma unroll
;     for (int i = 0; i < 4; ++i) {
;       const int id = tid + 512 * i;
;       c0f[i] = *(const uint4*)(Cf + (id >> 4) * 128 + (id & 15) * 8);
	v_lshlrev_b32_e32 v0, 16, v78
	v_and_b32_e32 v1, 0xffff0000, v78
	v_pk_mul_f32 v[212:213], v[6:7], v[142:143]
	v_lshlrev_b32_e32 v2, 16, v79
	v_and_b32_e32 v3, 0xffff0000, v79
	v_pk_mul_f32 v[214:215], v[6:7], v[144:145]
	v_lshlrev_b32_e32 v230, 16, v80
	v_and_b32_e32 v231, 0xffff0000, v80
	v_pk_mul_f32 v[216:217], v[6:7], v[146:147]
	v_lshlrev_b32_e32 v232, 16, v81
	v_and_b32_e32 v233, 0xffff0000, v81
	v_pk_mul_f32 v[218:219], v[6:7], v[148:149]
	v_pk_fma_f32 v[204:205], v[212:213], v[0:1], 0 op_sel_hi:[1,1,0]
	v_pk_fma_f32 v[206:207], v[214:215], v[2:3], 0 op_sel_hi:[1,1,0]
	v_pk_fma_f32 v[208:209], v[216:217], v[230:231], 0 op_sel_hi:[1,1,0]
	v_pk_fma_f32 v[210:211], v[218:219], v[232:233], 0 op_sel_hi:[1,1,0]
	v_lshlrev_b32_e32 v0, 16, v82
	v_and_b32_e32 v1, 0xffff0000, v82
	v_pk_mul_f32 v[212:213], v[8:9], v[150:151]
	v_lshlrev_b32_e32 v2, 16, v83
	v_and_b32_e32 v3, 0xffff0000, v83
	v_pk_mul_f32 v[214:215], v[8:9], v[152:153]
	v_lshlrev_b32_e32 v230, 16, v84
	v_and_b32_e32 v231, 0xffff0000, v84
	v_pk_mul_f32 v[216:217], v[8:9], v[154:155]
	v_lshlrev_b32_e32 v232, 16, v85
	v_and_b32_e32 v233, 0xffff0000, v85
	v_pk_mul_f32 v[218:219], v[8:9], v[156:157]
	v_pk_fma_f32 v[204:205], v[212:213], v[0:1], v[204:205]
	v_pk_fma_f32 v[206:207], v[214:215], v[2:3], v[206:207]
	v_pk_fma_f32 v[208:209], v[216:217], v[230:231], v[208:209]
	v_pk_fma_f32 v[210:211], v[218:219], v[232:233], v[210:211]
	v_lshlrev_b32_e32 v0, 16, v86
	v_and_b32_e32 v1, 0xffff0000, v86
	v_pk_mul_f32 v[212:213], v[10:11], v[158:159]
	v_lshlrev_b32_e32 v2, 16, v87
	v_and_b32_e32 v3, 0xffff0000, v87
	v_pk_mul_f32 v[214:215], v[10:11], v[160:161]
	v_lshlrev_b32_e32 v230, 16, v88
	v_and_b32_e32 v231, 0xffff0000, v88
	v_pk_mul_f32 v[216:217], v[10:11], v[162:163]
	v_lshlrev_b32_e32 v232, 16, v89
	v_and_b32_e32 v233, 0xffff0000, v89
	v_pk_mul_f32 v[218:219], v[10:11], v[164:165]
	v_pk_fma_f32 v[204:205], v[212:213], v[0:1], v[204:205]
	v_pk_fma_f32 v[206:207], v[214:215], v[2:3], v[206:207]
	v_pk_fma_f32 v[208:209], v[216:217], v[230:231], v[208:209]
	v_pk_fma_f32 v[210:211], v[218:219], v[232:233], v[210:211]
	v_lshlrev_b32_e32 v0, 16, v90
	v_and_b32_e32 v1, 0xffff0000, v90
	v_pk_mul_f32 v[212:213], v[12:13], v[166:167]
	v_lshlrev_b32_e32 v2, 16, v91
	v_and_b32_e32 v3, 0xffff0000, v91
	v_pk_mul_f32 v[214:215], v[12:13], v[168:169]
	v_lshlrev_b32_e32 v230, 16, v92
	v_and_b32_e32 v231, 0xffff0000, v92
	v_pk_mul_f32 v[216:217], v[12:13], v[170:171]
	v_lshlrev_b32_e32 v232, 16, v93
	v_and_b32_e32 v233, 0xffff0000, v93
	v_pk_mul_f32 v[218:219], v[12:13], v[172:173]
	v_pk_fma_f32 v[204:205], v[212:213], v[0:1], v[204:205]
	v_pk_fma_f32 v[206:207], v[214:215], v[2:3], v[206:207]
	v_pk_fma_f32 v[208:209], v[216:217], v[230:231], v[208:209]
	v_pk_fma_f32 v[210:211], v[218:219], v[232:233], v[210:211]
	v_mul_f32_e32 v212, 0xbfb8aa3b, v204
	v_mul_f32_e32 v213, 0xbfb8aa3b, v205
	v_mul_f32_e32 v214, 0xbfb8aa3b, v206
	v_mul_f32_e32 v215, 0xbfb8aa3b, v207
	v_mul_f32_e32 v216, 0xbfb8aa3b, v208
	v_mul_f32_e32 v217, 0xbfb8aa3b, v209
	v_mul_f32_e32 v218, 0xbfb8aa3b, v210
	v_mul_f32_e32 v219, 0xbfb8aa3b, v211
	v_exp_f32_e32 v212, v212
	v_exp_f32_e32 v213, v213
	v_exp_f32_e32 v214, v214
	v_exp_f32_e32 v215, v215
	v_exp_f32_e32 v216, v216
	v_exp_f32_e32 v217, v217
	v_exp_f32_e32 v218, v218
	v_exp_f32_e32 v219, v219
	v_add_f32_e32 v212, 1.0, v212
	v_add_f32_e32 v213, 1.0, v213
	v_add_f32_e32 v214, 1.0, v214
	v_add_f32_e32 v215, 1.0, v215
	v_add_f32_e32 v216, 1.0, v216
	v_add_f32_e32 v217, 1.0, v217
	v_add_f32_e32 v218, 1.0, v218
	v_add_f32_e32 v219, 1.0, v219
	v_rcp_f32_e32 v212, v212
	v_rcp_f32_e32 v213, v213
	v_rcp_f32_e32 v214, v214
	v_rcp_f32_e32 v215, v215
	v_rcp_f32_e32 v216, v216
	v_rcp_f32_e32 v217, v217
	v_rcp_f32_e32 v218, v218
	v_rcp_f32_e32 v219, v219
	s_nop 0
	v_pk_mul_f32 v[204:205], v[204:205], v[212:213]
	v_pk_mul_f32 v[206:207], v[206:207], v[214:215]
	v_pk_mul_f32 v[208:209], v[208:209], v[216:217]
	v_pk_mul_f32 v[210:211], v[210:211], v[218:219]
	v_pk_mul_f32 v[204:205], v[204:205], s[6:7] op_sel_hi:[1,0]
	v_pk_mul_f32 v[206:207], v[206:207], s[6:7] op_sel_hi:[1,0]
	v_pk_mul_f32 v[208:209], v[208:209], s[6:7] op_sel_hi:[1,0]
	v_pk_mul_f32 v[210:211], v[210:211], s[6:7] op_sel_hi:[1,0]
	v_cvt_pk_bf16_f32 v234, v204, v205
	v_cvt_pk_bf16_f32 v235, v206, v207
	v_cvt_pk_bf16_f32 v236, v208, v209
	v_cvt_pk_bf16_f32 v237, v210, v211
	ds_write_b128 v29, v[234:237] offset:192
	s_mul_i32 s0, s12, 18
	s_add_i32 s0, s0, s20
	s_ashr_i32 s1, s0, 31
	s_lshl_b64 s[0:1], s[0:1], 15
	v_lshlrev_b32_e32 v2, 3, v197
	s_add_u32 s0, s82, s0
	v_and_b32_e32 v0, 0x78, v2
	v_and_b32_e32 v210, 0xffffff80, v2
	s_addc_u32 s1, s83, s1
	v_lshlrev_b32_e32 v192, 1, v0
	v_add_u32_e32 v212, 0x1000, v210
	v_add_u32_e32 v214, 0x2000, v210
	v_add_u32_e32 v216, 0x3000, v210
	v_lshl_add_u64 v[0:1], s[0:1], 0, v[192:193]
	v_ashrrev_i32_e32 v211, 31, v210
	v_ashrrev_i32_e32 v213, 31, v212
	v_ashrrev_i32_e32 v215, 31, v214
	v_ashrrev_i32_e32 v217, 31, v216
	v_lshl_add_u64 v[204:205], v[210:211], 1, v[0:1]
	v_lshl_add_u64 v[206:207], v[212:213], 1, v[0:1]
	v_lshl_add_u64 v[208:209], v[214:215], 1, v[0:1]
	v_lshl_add_u64 v[218:219], v[216:217], 1, v[0:1]
	v_min_u32_e32 v0, s22, v199
	v_add_u32_e32 v0, -1, v0
	v_cmp_lt_i32_e32 vcc, 0, v199
	v_add_u32_e32 v1, 1, v199
	v_min_u32_e32 v1, s22, v1
	v_cndmask_b32_e32 v0, 0, v0, vcc
	v_add_u32_e32 v1, -1, v1
	v_cmp_lt_i32_e64 s[0:1], -1, v199
	v_add_u32_e32 v243, 2, v199
	v_lshlrev_b32_e32 v4, 6, v0
	v_cndmask_b32_e64 v1, 0, v1, s[0:1]
	v_min_u32_e32 v2, s22, v243
	v_and_b32_e32 v4, 0x7c0, v4
	v_ashrrev_i32_e32 v5, 5, v0
	v_add_u32_e32 v2, -1, v2
	v_cmp_lt_i32_e64 s[0:1], -2, v199
; __device__ __forceinline__ int sidx(int dir, int b, int h, int n) { return ((dir * 8 + b) * 4 + h) * 18 + n; }
; __device__ void ml_out_tile(unsigned char* lds, const Params& p, int l, int b, int h, int n) {
;     ...
;   uint4 c0f[4];
;   {
;     const bf16_t* Cf = Cst + (size_t)sidx(0, b, h, n) * 16384;
; #pragma unroll
;     for (int i = 0; i < 4; ++i) {
;       const int id = tid + 512 * i;
;       c0f[i] = *(const uint4*)(Cf + (id >> 4) * 128 + (id & 15) * 8);
;     }
;   }
;   bf16x8 qf[4];
; #pragma unroll
;   for (int ks = 0; ks < 4; ++ks) {
;     const int ec = ks * 4 + lg;
;     float q8[8];
;     ml_conv8(z, wc, 768 + h * 128 + ec * 8, h * 128 + ec * 8, b, isctx, L, p0 + t, q8);
;     const uint4 pk = pack8(q8);
;     qf[ks] = __builtin_bit_cast(bf16x8, pk);
;   }
; #pragma unroll
;   for (int i = 0; i < 4; ++i) {
;     const int id = tid + 512 * i;
;     *(uint4*)(C0s + (id >> 4) * 136 + (id & 15) * 8) = c0f[i];
;   }
	v_add_u32_e32 v244, 3, v199
	v_add3_u32 v4, v4, v5, v27
	v_add_u32_e32 v5, v26, v0
	v_lshlrev_b32_e32 v0, 6, v1
	v_cndmask_b32_e64 v2, 0, v2, s[0:1]
	v_min_u32_e32 v3, s22, v244
	v_and_b32_e32 v0, 0x7c0, v0
	v_ashrrev_i32_e32 v6, 5, v1
	v_add_u32_e32 v3, -1, v3
	v_cmp_lt_i32_e64 s[2:3], -3, v199
	v_add3_u32 v6, v0, v6, v27
	v_lshlrev_b32_e32 v0, 6, v2
	v_bfe_u32 v242, v197, 4, 2
	v_cndmask_b32_e64 v3, 0, v3, s[2:3]
	v_add_u32_e32 v7, v26, v1
	v_and_b32_e32 v0, 0x7c0, v0
	v_ashrrev_i32_e32 v1, 5, v2
	v_lshlrev_b32_e32 v200, 3, v242
	v_add3_u32 v8, v0, v1, v27
	v_lshlrev_b32_e32 v0, 6, v3
	v_and_b32_e32 v0, 0x7c0, v0
	v_ashrrev_i32_e32 v1, 5, v3
	v_add_u32_e32 v20, s96, v200
	v_add3_u32 v10, v0, v1, v27
	v_lshlrev_b32_e32 v0, 1, v20
	v_mov_b32_e32 v1, v193
	v_lshl_add_u64 v[0:1], s[88:89], 0, v[0:1]
	v_cndmask_b32_e64 v14, v4, v5, s[38:39]
	v_add_u32_e32 v9, v26, v2
	v_add_u32_e32 v11, v26, v3
	v_mad_i64_i32 v[2:3], s[4:5], v14, s92, v[0:1]
	v_cndmask_b32_e64 v15, v6, v7, s[38:39]
	v_or_b32_e32 v12, s96, v200
	global_load_dwordx4 v[184:187], v[2:3], off offset:1536
	v_mad_i64_i32 v[2:3], s[4:5], v15, s92, v[0:1]
	v_cndmask_b32_e64 v16, v8, v9, s[38:39]
	v_cndmask_b32_e64 v18, v10, v11, s[38:39]
	global_load_dwordx4 v[188:191], v[2:3], off offset:1536
	v_mad_i64_i32 v[2:3], s[4:5], v16, s92, v[0:1]
	v_mad_i64_i32 v[0:1], s[4:5], v18, s92, v[0:1]
	v_lshlrev_b32_e32 v4, 2, v12
	v_mov_b32_e32 v5, v193
	v_lshl_add_u64 v[6:7], s[14:15], 0, v[4:5]
	s_mov_b64 s[4:5], 0x1000
	v_lshl_add_u64 v[8:9], v[6:7], 0, s[4:5]
	s_mov_b64 s[4:5], 0x2000
	v_lshl_add_u64 v[10:11], v[6:7], 0, s[4:5]
	s_mov_b64 s[4:5], 0x3000
	global_load_dwordx4 v[176:179], v[2:3], off offset:1536
	global_load_dwordx4 v[180:183], v[0:1], off offset:1536
	v_lshl_add_u64 v[12:13], v[6:7], 0, s[4:5]
	global_load_dwordx4 v[0:3], v4, s[14:15] offset:16
	global_load_dwordx4 v[160:163], v4, s[14:15]
	v_add_co_u32_e64 v4, s[4:5], s8, v6
	s_add_i32 s6, s96, 0x300
	s_nop 0
	v_addc_co_u32_e64 v5, s[4:5], 0, v7, s[4:5]
	global_load_dwordx4 v[164:167], v[4:5], off offset:-4096
	global_load_dwordx4 v[148:151], v[8:9], off offset:16
	global_load_dwordx4 v[168:171], v[4:5], off
	global_load_dwordx4 v[152:155], v[10:11], off offset:16
	v_add_co_u32_e64 v4, s[4:5], s9, v6
	v_lshlrev_b32_e32 v24, 2, v20
	s_nop 0
	v_addc_co_u32_e64 v5, s[4:5], 0, v7, s[4:5]
	global_load_dwordx4 v[172:175], v[4:5], off
	global_load_dwordx4 v[156:159], v[12:13], off offset:16
	v_add_lshl_u32 v4, v200, s6, 1
	v_mov_b32_e32 v5, v193
	v_lshl_add_u64 v[4:5], s[88:89], 0, v[4:5]
	v_mad_i64_i32 v[12:13], s[4:5], v14, s92, v[4:5]
	v_mad_i64_i32 v[14:15], s[4:5], v15, s92, v[4:5]
	v_mad_i64_i32 v[16:17], s[4:5], v16, s92, v[4:5]
	v_mad_i64_i32 v[18:19], s[4:5], v18, s92, v[4:5]
	v_mov_b32_e32 v25, v193
	v_lshl_add_u64 v[20:21], s[14:15], 0, v[24:25]
	s_mov_b64 s[4:5], 0x1080
	v_lshl_add_u64 v[8:9], v[20:21], 0, s[4:5]
	s_mov_b64 s[4:5], 0x2080
	v_lshl_add_u64 v[10:11], v[20:21], 0, s[4:5]
	s_mov_b64 s[4:5], 0x3080
	v_lshl_add_u64 v[22:23], v[20:21], 0, s[4:5]
	v_add_co_u32_e64 v26, s[4:5], s7, v20
	global_load_dwordx4 v[144:147], v[12:13], off offset:64
	global_load_dwordx4 v[140:143], v[14:15], off offset:64
	v_addc_co_u32_e64 v27, s[4:5], 0, v21, s[4:5]
	v_add_co_u32_e64 v28, s[4:5], s8, v20
	global_load_dwordx4 v[136:139], v[16:17], off offset:64
	global_load_dwordx4 v[132:135], v[18:19], off offset:64
	v_addc_co_u32_e64 v29, s[4:5], 0, v21, s[4:5]
	v_add_co_u32_e64 v30, s[4:5], s9, v20
	global_load_dwordx4 v[4:7], v24, s[14:15] offset:144
	global_load_dwordx4 v[120:123], v24, s[14:15] offset:128
	v_addc_co_u32_e64 v31, s[4:5], 0, v21, s[4:5]
	s_mov_b64 s[4:5], 0x1100
	global_load_dwordx4 v[116:119], v[26:27], off offset:128
	global_load_dwordx4 v[104:107], v[8:9], off offset:16
	v_lshl_add_u64 v[8:9], v[20:21], 0, s[4:5]
	s_mov_b64 s[4:5], 0x2100
	global_load_dwordx4 v[124:127], v[28:29], off offset:128
	global_load_dwordx4 v[108:111], v[10:11], off offset:16
	global_load_dwordx4 v[128:131], v[30:31], off offset:128
	global_load_dwordx4 v[112:115], v[22:23], off offset:16
	global_load_dwordx4 v[100:103], v[12:13], off offset:128
	global_load_dwordx4 v[96:99], v[14:15], off offset:128
	global_load_dwordx4 v[92:95], v[16:17], off offset:128
	global_load_dwordx4 v[88:91], v[18:19], off offset:128
	v_lshl_add_u64 v[22:23], v[20:21], 0, s[4:5]
	s_mov_b64 s[4:5], 0x3100
	v_lshl_add_u64 v[32:33], v[20:21], 0, s[4:5]
	s_mov_b64 s[4:5], 0x1180
	global_load_dwordx4 v[60:63], v24, s[14:15] offset:272
	global_load_dwordx4 v[76:79], v24, s[14:15] offset:256
	global_load_dwordx4 v[72:75], v[26:27], off offset:256
	s_nop 0
	global_load_dwordx4 v[8:11], v[8:9], off offset:16
	s_nop 0
	global_load_dwordx4 v[80:83], v[28:29], off offset:256
	global_load_dwordx4 v[68:71], v[22:23], off offset:16
	global_load_dwordx4 v[84:87], v[30:31], off offset:256
	global_load_dwordx4 v[64:67], v[32:33], off offset:16
	global_load_dwordx4 v[56:59], v[12:13], off offset:192
	global_load_dwordx4 v[52:55], v[14:15], off offset:192
	global_load_dwordx4 v[48:51], v[16:17], off offset:192
	global_load_dwordx4 v[44:47], v[18:19], off offset:192
	v_lshl_add_u64 v[12:13], v[20:21], 0, s[4:5]
	s_mov_b64 s[4:5], 0x2180
	v_lshl_add_u64 v[14:15], v[20:21], 0, s[4:5]
	s_mov_b64 s[4:5], 0x3180
	v_lshl_add_u64 v[230:231], v[20:21], 0, s[4:5]
	global_load_dwordx4 v[20:23], v24, s[14:15] offset:400
	global_load_dwordx4 v[40:43], v24, s[14:15] offset:384
	global_load_dwordx4 v[36:39], v[26:27], off offset:384
	s_nop 0
	global_load_dwordx4 v[24:27], v[12:13], off offset:16
	global_load_dwordx4 v[32:35], v[28:29], off offset:384
	global_load_dwordx4 v[16:19], v[14:15], off offset:16
	s_nop 0
	global_load_dwordx4 v[28:31], v[30:31], off offset:384
	s_nop 0
	global_load_dwordx4 v[12:15], v[230:231], off offset:16
	v_add_u32_e32 v226, 0, v192
	global_load_dwordx4 v[230:233], v[204:205], off
	v_mad_u64_u32 v[202:203], s[4:5], v202, s93, v[226:227]
	v_add_u32_e32 v203, 0x200, v197
	v_lshrrev_b32_e32 v203, 4, v203
	v_mad_u64_u32 v[204:205], s[4:5], v203, s93, v[226:227]
	v_add_u32_e32 v203, 0x400, v197
	v_lshrrev_b32_e32 v203, 4, v203
	s_waitcnt vmcnt(0)
	ds_write_b128 v202, v[230:233]
	global_load_dwordx4 v[230:233], v[206:207], off
	v_mad_u64_u32 v[206:207], s[4:5], v203, s93, v[226:227]
	v_add_u32_e32 v203, 0x600, v197
	v_lshrrev_b32_e32 v203, 4, v203
	s_waitcnt vmcnt(0)
	ds_write_b128 v204, v[230:233]
	global_load_dwordx4 v[230:233], v[208:209], off
	v_mad_u64_u32 v[208:209], s[4:5], v203, s93, v[226:227]
	v_mov_b32_e32 v203, v195
	s_waitcnt vmcnt(0)
	ds_write_b128 v206, v[230:233]
	global_load_dwordx4 v[230:233], v[218:219], off
	s_waitcnt vmcnt(0)
	ds_write_b128 v208, v[230:233]
	s_nop 0
	v_cmp_gt_i32_e64 s[4:5], s91, v203
	s_and_saveexec_b64 s[10:11], s[4:5]
	s_cbranch_execz .LBB0_733
; __device__ __forceinline__ int opaque_tid() { int t = threadIdx.x; asm volatile("" : "+v"(t)); return t; }
; __device__ __forceinline__ float fexp(float x) { return __expf(x); }
; __device__ __forceinline__ float logsig(float x) { return fminf(x, 0.f) - __logf(1.f + fexp(-fabsf(x))); }
; __device__ __forceinline__ void ml_prep(float* vec, const float* g4, float* scal, int b, int n, int h, bool outmode) {
;   const int tid = opaque_tid();
;   if (tid < 128) {
;     vec[0 * 128 + tid] = g4[0];
;     vec[1 * 128 + tid] = logsig(g4[1]);
;     vec[2 * 128 + tid] = g4[2];
;     vec[3 * 128 + tid] = logsig(g4[3]);
;   }
	s_mov_b32 s15, 0xbfb8aa3b
	v_mul_f32_e64 v209, |v224|, s15
	v_exp_f32_e32 v209, v209
	s_mov_b32 s13, 0x800000
	s_mov_b32 s16, 0x3f317217
	s_mov_b32 s14, 0x7f800000
	v_add_f32_e32 v209, 1.0, v209
	v_cmp_gt_f32_e64 s[6:7], s13, v209
	v_mov_b32_e32 v219, 0x41b17218
	v_max_f32_e32 v207, v224, v224
	v_cndmask_b32_e64 v218, 0, 32, s[6:7]
	v_ldexp_f32 v209, v209, v218
	v_log_f32_e32 v209, v209
	v_min_f32_e32 v207, 0, v207
	v_lshl_add_u32 v205, v203, 2, 0
	v_add_u32_e32 v205, 0x22000, v205
	v_mul_f32_e32 v218, 0x3f317217, v209
	v_fma_f32 v218, v209, s16, -v218
	v_fmac_f32_e32 v218, 0x3377d1cf, v209
	v_fmac_f32_e32 v218, 0x3f317217, v209
	v_cmp_lt_f32_e64 s[8:9], |v209|, s14
	s_nop 1
	v_cndmask_b32_e64 v209, v209, v218, s[8:9]
	v_cndmask_b32_e64 v218, 0, v219, s[6:7]
	v_sub_f32_e32 v209, v209, v218
	v_sub_f32_e32 v207, v207, v209
	v_mul_f32_e64 v209, |v220|, s15
	v_exp_f32_e32 v209, v209
	ds_write2st64_b32 v205, v222, v207 offset1:2
	v_max_f32_e32 v207, v220, v220
	v_min_f32_e32 v207, 0, v207
	v_add_f32_e32 v209, 1.0, v209
	v_cmp_gt_f32_e64 s[6:7], s13, v209
	s_nop 1
	v_cndmask_b32_e64 v218, 0, 32, s[6:7]
	v_ldexp_f32 v209, v209, v218
	v_log_f32_e32 v209, v209
	s_nop 0
	v_mul_f32_e32 v218, 0x3f317217, v209
	v_fma_f32 v218, v209, s16, -v218
	v_fmac_f32_e32 v218, 0x3377d1cf, v209
	v_fmac_f32_e32 v218, 0x3f317217, v209
	v_cmp_lt_f32_e64 s[8:9], |v209|, s14
	s_nop 1
	v_cndmask_b32_e64 v209, v209, v218, s[8:9]
	v_cndmask_b32_e64 v218, 0, v219, s[6:7]
	v_sub_f32_e32 v209, v209, v218
	v_sub_f32_e32 v207, v207, v209
	ds_write2st64_b32 v205, v201, v207 offset0:4 offset1:6

; __device__ __forceinline__ float fexp(float x) { return __expf(x); }
; __device__ void ml_out_tile(unsigned char* lds, const Params& p, int l, int b, int h, int n) {
;     ...
;     {
;       const float rv = ROWV[t];
; #pragma unroll
;       for (int sf = 0; sf < 8; ++sf) {
;         f32x4 acc = (f32x4){0.f, 0.f, 0.f, 0.f};
; #pragma unroll
;         for (int ks = 0; ks < 4; ++ks) {
;           const bf16x8 kf = ldfrag(Ks + (sf * 16 + lr) * 136 + ks * 32 + lg * 8);
;           acc = mfma16(kf, qf[ks], acc);
;         }
;         float pv[4];
; #pragma unroll
;         for (int j = 0; j < 4; ++j) {
;           const int s = sf * 16 + lg * 4 + j;
;           const bool ok = (dir == 0) ? (s <= t) : (s >= t);
;           pv[j] = ok ? acc[j] * fexp(rv + COLV[s]) : 0.f;
;         }
;         uint2 u; u.x = pack2(pv[0], pv[1]); u.y = pack2(pv[2], pv[3]);
;         *(uint2*)(Ps + t * 136 + sf * 16 + lg * 4) = u;
;       }
;     }
.LBB0_742:
	s_lshl_b32 s76, s33, 11
	s_add_i32 s76, s76, 0x22000
	s_lshl_b32 s10, s33, 1
	s_sub_i32 s10, 1, s10
	s_lshl_b32 s11, s10, 1
	s_mul_i32 s12, s10, 3
	s_lshl_b32 s13, s10, 4
	v_lshl_add_u32 v100, v240, 2, s76
	v_lshl_add_u32 v37, v68, 2, s76
	v_add_u32_e32 v38, v110, v200
	v_sub_u32_e32 v39, v240, v68
	v_mul_lo_u32 v39, v39, s10
	ds_read_b128 v[158:161], v124 offset:34816
	ds_read_b128 v[162:165], v124 offset:34880
	ds_read_b128 v[166:169], v124 offset:34944
	ds_read_b128 v[170:173], v124 offset:35008
	ds_read_b32 v36, v100 offset:3072
	ds_read_b128 v[126:129], v37 offset:3584
	ds_read_b128 v[130:133], v37 offset:3648
	ds_read_b128 v[134:137], v37 offset:3712
	ds_read_b128 v[138:141], v37 offset:3776
	ds_read_b128 v[174:177], v124 offset:39168
	ds_read_b128 v[178:181], v124 offset:39232
	ds_read_b128 v[182:185], v124 offset:39296
	ds_read_b128 v[186:189], v124 offset:39360
	s_waitcnt lgkmcnt(9)
	v_mfma_f32_16x16x32_bf16 v[32:35], v[158:161], v[0:3], 0
	v_mfma_f32_16x16x32_bf16 v[32:35], v[162:165], v[4:7], v[32:35]
	v_mfma_f32_16x16x32_bf16 v[32:35], v[166:169], v[8:11], v[32:35]
	v_mfma_f32_16x16x32_bf16 v[32:35], v[170:173], v[12:15], v[32:35]
	ds_read_b128 v[142:145], v37 offset:3840
	ds_read_b128 v[146:149], v37 offset:3904
	ds_read_b128 v[150:153], v37 offset:3968
	ds_read_b128 v[154:157], v37 offset:4032
	s_waitcnt lgkmcnt(8)
	v_add_f32_e32 v102, v36, v126
	v_add_f32_e32 v103, v36, v127
	v_add_f32_e32 v104, v36, v128
	v_add_f32_e32 v105, v36, v129
	v_mul_f32_e32 v102, 0x3fb8aa3b, v102
	v_mul_f32_e32 v103, 0x3fb8aa3b, v103
	v_mul_f32_e32 v104, 0x3fb8aa3b, v104
	v_mul_f32_e32 v105, 0x3fb8aa3b, v105
	v_exp_f32_e32 v102, v102
	v_exp_f32_e32 v103, v103
	v_exp_f32_e32 v104, v104
	v_exp_f32_e32 v105, v105
	v_cmp_le_i32_e64 s[2:3], 0, v39
	v_cmp_le_i32_e64 s[4:5], s10, v39
	v_cmp_le_i32_e64 s[6:7], s11, v39
	v_cmp_le_i32_e64 s[8:9], s12, v39
	v_mul_f32_e32 v32, v32, v102
	v_mul_f32_e32 v33, v33, v103
	v_mul_f32_e32 v34, v34, v104
	v_mul_f32_e32 v35, v35, v105
	v_cndmask_b32_e64 v32, 0, v32, s[2:3]
	v_cndmask_b32_e64 v33, 0, v33, s[4:5]
	v_cndmask_b32_e64 v34, 0, v34, s[6:7]
	v_cndmask_b32_e64 v35, 0, v35, s[8:9]
	v_subrev_u32_e32 v39, s13, v39
	v_cvt_pk_bf16_f32 v102, v32, v33
	v_cvt_pk_bf16_f32 v103, v34, v35
	ds_write_b64 v38, v[102:103]
	ds_read_b128 v[158:161], v124 offset:43520
	ds_read_b128 v[162:165], v124 offset:43584
	ds_read_b128 v[166:169], v124 offset:43648
	ds_read_b128 v[170:173], v124 offset:43712
	s_waitcnt lgkmcnt(9)
	v_mfma_f32_16x16x32_bf16 v[32:35], v[174:177], v[0:3], 0
	v_mfma_f32_16x16x32_bf16 v[32:35], v[178:181], v[4:7], v[32:35]
	v_mfma_f32_16x16x32_bf16 v[32:35], v[182:185], v[8:11], v[32:35]
	v_mfma_f32_16x16x32_bf16 v[32:35], v[186:189], v[12:15], v[32:35]
	v_add_f32_e32 v102, v36, v130
	v_add_f32_e32 v103, v36, v131
	v_add_f32_e32 v104, v36, v132
	v_add_f32_e32 v105, v36, v133
	v_mul_f32_e32 v102, 0x3fb8aa3b, v102
	v_mul_f32_e32 v103, 0x3fb8aa3b, v103
	v_mul_f32_e32 v104, 0x3fb8aa3b, v104
	v_mul_f32_e32 v105, 0x3fb8aa3b, v105
	v_exp_f32_e32 v102, v102
	v_exp_f32_e32 v103, v103
	v_exp_f32_e32 v104, v104
	v_exp_f32_e32 v105, v105
	v_cmp_le_i32_e64 s[2:3], 0, v39
	v_cmp_le_i32_e64 s[4:5], s10, v39
	v_cmp_le_i32_e64 s[6:7], s11, v39
	v_cmp_le_i32_e64 s[8:9], s12, v39
	v_mul_f32_e32 v32, v32, v102
	v_mul_f32_e32 v33, v33, v103
	v_mul_f32_e32 v34, v34, v104
	v_mul_f32_e32 v35, v35, v105
	v_cndmask_b32_e64 v32, 0, v32, s[2:3]
	v_cndmask_b32_e64 v33, 0, v33, s[4:5]
	v_cndmask_b32_e64 v34, 0, v34, s[6:7]
	v_cndmask_b32_e64 v35, 0, v35, s[8:9]
	v_subrev_u32_e32 v39, s13, v39
	v_cvt_pk_bf16_f32 v102, v32, v33
	v_cvt_pk_bf16_f32 v103, v34, v35
	ds_write_b64 v38, v[102:103] offset:32
	ds_read_b128 v[174:177], v124 offset:47872
	ds_read_b128 v[178:181], v124 offset:47936
	ds_read_b128 v[182:185], v124 offset:48000
	ds_read_b128 v[186:189], v124 offset:48064
	s_waitcnt lgkmcnt(5)
	v_mfma_f32_16x16x32_bf16 v[32:35], v[158:161], v[0:3], 0
	v_mfma_f32_16x16x32_bf16 v[32:35], v[162:165], v[4:7], v[32:35]
	v_mfma_f32_16x16x32_bf16 v[32:35], v[166:169], v[8:11], v[32:35]
	v_mfma_f32_16x16x32_bf16 v[32:35], v[170:173], v[12:15], v[32:35]
	v_add_f32_e32 v102, v36, v134
	v_add_f32_e32 v103, v36, v135
	v_add_f32_e32 v104, v36, v136
	v_add_f32_e32 v105, v36, v137
	v_mul_f32_e32 v102, 0x3fb8aa3b, v102
	v_mul_f32_e32 v103, 0x3fb8aa3b, v103
	v_mul_f32_e32 v104, 0x3fb8aa3b, v104
	v_mul_f32_e32 v105, 0x3fb8aa3b, v105
	v_exp_f32_e32 v102, v102
	v_exp_f32_e32 v103, v103
	v_exp_f32_e32 v104, v104
	v_exp_f32_e32 v105, v105
	v_cmp_le_i32_e64 s[2:3], 0, v39
	v_cmp_le_i32_e64 s[4:5], s10, v39
	v_cmp_le_i32_e64 s[6:7], s11, v39
	v_cmp_le_i32_e64 s[8:9], s12, v39
	v_mul_f32_e32 v32, v32, v102
	v_mul_f32_e32 v33, v33, v103
	v_mul_f32_e32 v34, v34, v104
	v_mul_f32_e32 v35, v35, v105
	v_cndmask_b32_e64 v32, 0, v32, s[2:3]
	v_cndmask_b32_e64 v33, 0, v33, s[4:5]
	v_cndmask_b32_e64 v34, 0, v34, s[6:7]
	v_cndmask_b32_e64 v35, 0, v35, s[8:9]
	v_subrev_u32_e32 v39, s13, v39
	v_cvt_pk_bf16_f32 v102, v32, v33
	v_cvt_pk_bf16_f32 v103, v34, v35
	ds_write_b64 v38, v[102:103] offset:64
	ds_read_b128 v[158:161], v124 offset:52224
	ds_read_b128 v[162:165], v124 offset:52288
	ds_read_b128 v[166:169], v124 offset:52352
	ds_read_b128 v[170:173], v124 offset:52416
	s_waitcnt lgkmcnt(5)
; __device__ __forceinline__ float fexp(float x) { return __expf(x); }
; __device__ void ml_out_tile(unsigned char* lds, const Params& p, int l, int b, int h, int n) {
;     ...
;     {
;       const float rv = ROWV[t];
; #pragma unroll
;       for (int sf = 0; sf < 8; ++sf) {
;         f32x4 acc = (f32x4){0.f, 0.f, 0.f, 0.f};
; #pragma unroll
;         for (int ks = 0; ks < 4; ++ks) {
;           const bf16x8 kf = ldfrag(Ks + (sf * 16 + lr) * 136 + ks * 32 + lg * 8);
;           acc = mfma16(kf, qf[ks], acc);
;         }
;         float pv[4];
; #pragma unroll
;         for (int j = 0; j < 4; ++j) {
;           const int s = sf * 16 + lg * 4 + j;
;           const bool ok = (dir == 0) ? (s <= t) : (s >= t);
;           pv[j] = ok ? acc[j] * fexp(rv + COLV[s]) : 0.f;
;         }
;         uint2 u; u.x = pack2(pv[0], pv[1]); u.y = pack2(pv[2], pv[3]);
;         *(uint2*)(Ps + t * 136 + sf * 16 + lg * 4) = u;
;       }
;     }
;     __syncthreads();
	v_mfma_f32_16x16x32_bf16 v[32:35], v[174:177], v[0:3], 0
	v_mfma_f32_16x16x32_bf16 v[32:35], v[178:181], v[4:7], v[32:35]
	v_mfma_f32_16x16x32_bf16 v[32:35], v[182:185], v[8:11], v[32:35]
	v_mfma_f32_16x16x32_bf16 v[32:35], v[186:189], v[12:15], v[32:35]
	v_add_f32_e32 v102, v36, v138
	v_add_f32_e32 v103, v36, v139
	v_add_f32_e32 v104, v36, v140
	v_add_f32_e32 v105, v36, v141
	v_mul_f32_e32 v102, 0x3fb8aa3b, v102
	v_mul_f32_e32 v103, 0x3fb8aa3b, v103
	v_mul_f32_e32 v104, 0x3fb8aa3b, v104
	v_mul_f32_e32 v105, 0x3fb8aa3b, v105
	v_exp_f32_e32 v102, v102
	v_exp_f32_e32 v103, v103
	v_exp_f32_e32 v104, v104
	v_exp_f32_e32 v105, v105
	v_cmp_le_i32_e64 s[2:3], 0, v39
	v_cmp_le_i32_e64 s[4:5], s10, v39
	v_cmp_le_i32_e64 s[6:7], s11, v39
	v_cmp_le_i32_e64 s[8:9], s12, v39
	v_mul_f32_e32 v32, v32, v102
	v_mul_f32_e32 v33, v33, v103
	v_mul_f32_e32 v34, v34, v104
	v_mul_f32_e32 v35, v35, v105
	v_cndmask_b32_e64 v32, 0, v32, s[2:3]
	v_cndmask_b32_e64 v33, 0, v33, s[4:5]
	v_cndmask_b32_e64 v34, 0, v34, s[6:7]
	v_cndmask_b32_e64 v35, 0, v35, s[8:9]
	v_subrev_u32_e32 v39, s13, v39
	v_cvt_pk_bf16_f32 v102, v32, v33
	v_cvt_pk_bf16_f32 v103, v34, v35
	ds_write_b64 v38, v[102:103] offset:96
	ds_read_b128 v[174:177], v124 offset:56576
	ds_read_b128 v[178:181], v124 offset:56640
	ds_read_b128 v[182:185], v124 offset:56704
	ds_read_b128 v[186:189], v124 offset:56768
	s_waitcnt lgkmcnt(5)
	v_mfma_f32_16x16x32_bf16 v[32:35], v[158:161], v[0:3], 0
	v_mfma_f32_16x16x32_bf16 v[32:35], v[162:165], v[4:7], v[32:35]
	v_mfma_f32_16x16x32_bf16 v[32:35], v[166:169], v[8:11], v[32:35]
	v_mfma_f32_16x16x32_bf16 v[32:35], v[170:173], v[12:15], v[32:35]
	v_add_f32_e32 v102, v36, v142
	v_add_f32_e32 v103, v36, v143
	v_add_f32_e32 v104, v36, v144
	v_add_f32_e32 v105, v36, v145
	v_mul_f32_e32 v102, 0x3fb8aa3b, v102
	v_mul_f32_e32 v103, 0x3fb8aa3b, v103
	v_mul_f32_e32 v104, 0x3fb8aa3b, v104
	v_mul_f32_e32 v105, 0x3fb8aa3b, v105
	v_exp_f32_e32 v102, v102
	v_exp_f32_e32 v103, v103
	v_exp_f32_e32 v104, v104
	v_exp_f32_e32 v105, v105
	v_cmp_le_i32_e64 s[2:3], 0, v39
	v_cmp_le_i32_e64 s[4:5], s10, v39
	v_cmp_le_i32_e64 s[6:7], s11, v39
	v_cmp_le_i32_e64 s[8:9], s12, v39
	v_mul_f32_e32 v32, v32, v102
	v_mul_f32_e32 v33, v33, v103
	v_mul_f32_e32 v34, v34, v104
	v_mul_f32_e32 v35, v35, v105
	v_cndmask_b32_e64 v32, 0, v32, s[2:3]
	v_cndmask_b32_e64 v33, 0, v33, s[4:5]
	v_cndmask_b32_e64 v34, 0, v34, s[6:7]
	v_cndmask_b32_e64 v35, 0, v35, s[8:9]
	v_subrev_u32_e32 v39, s13, v39
	v_cvt_pk_bf16_f32 v102, v32, v33
	v_cvt_pk_bf16_f32 v103, v34, v35
	ds_write_b64 v38, v[102:103] offset:128
	ds_read_b128 v[158:161], v124 offset:60928
	ds_read_b128 v[162:165], v124 offset:60992
	ds_read_b128 v[166:169], v124 offset:61056
	ds_read_b128 v[170:173], v124 offset:61120
	s_waitcnt lgkmcnt(5)
	v_mfma_f32_16x16x32_bf16 v[32:35], v[174:177], v[0:3], 0
	v_mfma_f32_16x16x32_bf16 v[32:35], v[178:181], v[4:7], v[32:35]
	v_mfma_f32_16x16x32_bf16 v[32:35], v[182:185], v[8:11], v[32:35]
	v_mfma_f32_16x16x32_bf16 v[32:35], v[186:189], v[12:15], v[32:35]
	v_add_f32_e32 v102, v36, v146
	v_add_f32_e32 v103, v36, v147
	v_add_f32_e32 v104, v36, v148
	v_add_f32_e32 v105, v36, v149
	v_mul_f32_e32 v102, 0x3fb8aa3b, v102
	v_mul_f32_e32 v103, 0x3fb8aa3b, v103
	v_mul_f32_e32 v104, 0x3fb8aa3b, v104
	v_mul_f32_e32 v105, 0x3fb8aa3b, v105
	v_exp_f32_e32 v102, v102
	v_exp_f32_e32 v103, v103
	v_exp_f32_e32 v104, v104
	v_exp_f32_e32 v105, v105
	v_cmp_le_i32_e64 s[2:3], 0, v39
	v_cmp_le_i32_e64 s[4:5], s10, v39
	v_cmp_le_i32_e64 s[6:7], s11, v39
	v_cmp_le_i32_e64 s[8:9], s12, v39
	v_mul_f32_e32 v32, v32, v102
	v_mul_f32_e32 v33, v33, v103
	v_mul_f32_e32 v34, v34, v104
	v_mul_f32_e32 v35, v35, v105
	v_cndmask_b32_e64 v32, 0, v32, s[2:3]
	v_cndmask_b32_e64 v33, 0, v33, s[4:5]
	v_cndmask_b32_e64 v34, 0, v34, s[6:7]
	v_cndmask_b32_e64 v35, 0, v35, s[8:9]
	v_subrev_u32_e32 v39, s13, v39
	v_cvt_pk_bf16_f32 v102, v32, v33
	v_cvt_pk_bf16_f32 v103, v34, v35
	ds_write_b64 v38, v[102:103] offset:160
	ds_read_b128 v[174:177], v124 offset:65280
	ds_read_b128 v[178:181], v124 offset:65344
	ds_read_b128 v[182:185], v124 offset:65408
	ds_read_b128 v[186:189], v124 offset:65472
	s_waitcnt lgkmcnt(5)
	v_mfma_f32_16x16x32_bf16 v[32:35], v[158:161], v[0:3], 0
	v_mfma_f32_16x16x32_bf16 v[32:35], v[162:165], v[4:7], v[32:35]
	v_mfma_f32_16x16x32_bf16 v[32:35], v[166:169], v[8:11], v[32:35]
	v_mfma_f32_16x16x32_bf16 v[32:35], v[170:173], v[12:15], v[32:35]
	v_add_f32_e32 v102, v36, v150
	v_add_f32_e32 v103, v36, v151
	v_add_f32_e32 v104, v36, v152
	v_add_f32_e32 v105, v36, v153
	v_mul_f32_e32 v102, 0x3fb8aa3b, v102
	v_mul_f32_e32 v103, 0x3fb8aa3b, v103
	v_mul_f32_e32 v104, 0x3fb8aa3b, v104
	v_mul_f32_e32 v105, 0x3fb8aa3b, v105
	v_exp_f32_e32 v102, v102
	v_exp_f32_e32 v103, v103
	v_exp_f32_e32 v104, v104
	v_exp_f32_e32 v105, v105
	v_cmp_le_i32_e64 s[2:3], 0, v39
	v_cmp_le_i32_e64 s[4:5], s10, v39
	v_cmp_le_i32_e64 s[6:7], s11, v39
	v_cmp_le_i32_e64 s[8:9], s12, v39
	v_mul_f32_e32 v32, v32, v102
	v_mul_f32_e32 v33, v33, v103
	v_mul_f32_e32 v34, v34, v104
	v_mul_f32_e32 v35, v35, v105
	v_cndmask_b32_e64 v32, 0, v32, s[2:3]
	v_cndmask_b32_e64 v33, 0, v33, s[4:5]
	v_cndmask_b32_e64 v34, 0, v34, s[6:7]
	v_cndmask_b32_e64 v35, 0, v35, s[8:9]
	v_subrev_u32_e32 v39, s13, v39
	v_cvt_pk_bf16_f32 v102, v32, v33
	v_cvt_pk_bf16_f32 v103, v34, v35
	ds_write_b64 v38, v[102:103] offset:192
	s_waitcnt lgkmcnt(1)
	v_mfma_f32_16x16x32_bf16 v[32:35], v[174:177], v[0:3], 0
	v_mfma_f32_16x16x32_bf16 v[32:35], v[178:181], v[4:7], v[32:35]
	v_mfma_f32_16x16x32_bf16 v[32:35], v[182:185], v[8:11], v[32:35]
	v_mfma_f32_16x16x32_bf16 v[32:35], v[186:189], v[12:15], v[32:35]
	v_add_f32_e32 v102, v36, v154
	v_add_f32_e32 v103, v36, v155
	v_add_f32_e32 v104, v36, v156
	v_add_f32_e32 v105, v36, v157
	v_mul_f32_e32 v102, 0x3fb8aa3b, v102
	v_mul_f32_e32 v103, 0x3fb8aa3b, v103
	v_mul_f32_e32 v104, 0x3fb8aa3b, v104
	v_mul_f32_e32 v105, 0x3fb8aa3b, v105
	v_exp_f32_e32 v102, v102
	v_exp_f32_e32 v103, v103
	v_exp_f32_e32 v104, v104
	v_exp_f32_e32 v105, v105
	v_cmp_le_i32_e64 s[2:3], 0, v39
	v_cmp_le_i32_e64 s[4:5], s10, v39
	v_cmp_le_i32_e64 s[6:7], s11, v39
	v_cmp_le_i32_e64 s[8:9], s12, v39
	v_mul_f32_e32 v32, v32, v102
	v_mul_f32_e32 v33, v33, v103
	v_mul_f32_e32 v34, v34, v104
	v_mul_f32_e32 v35, v35, v105
	v_cndmask_b32_e64 v32, 0, v32, s[2:3]
	v_cndmask_b32_e64 v33, 0, v33, s[4:5]
	v_cndmask_b32_e64 v34, 0, v34, s[6:7]
	v_cndmask_b32_e64 v35, 0, v35, s[8:9]
	v_cvt_pk_bf16_f32 v102, v32, v33
	v_cvt_pk_bf16_f32 v103, v34, v35
	ds_write_b64 v38, v[102:103] offset:224
	s_waitcnt lgkmcnt(0)
	s_barrier
; __device__ void ml_out_tile(unsigned char* lds, const Params& p, int l, int b, int h, int n) {
;     ...
;     if (tid < 128) {
;       float rs = 0.f;
; #pragma unroll
;       for (int c8 = 0; c8 < 16; ++c8) {
;         float f[8];
;         unpack8(*(const uint4*)(Ps + tid * 136 + c8 * 8), f);
; #pragma unroll
;         for (int e = 0; e < 8; ++e) rs += f[e];
;       }
	s_mov_b64 vcc, exec
	v_readlane_b32 s70, v254, 26
	v_readlane_b32 s71, v254, 27
	s_and_b64 s[70:71], vcc, s[70:71]
	s_mov_b64 exec, s[70:71]
	s_cbranch_execz .LBB0_808
	ds_read_b128 v[32:35], v112
	ds_read_b128 v[36:39], v112 offset:16
	ds_read_b128 v[102:105], v112 offset:32
	ds_read_b128 v[126:129], v112 offset:48
	s_waitcnt lgkmcnt(3)
	v_lshlrev_b32_e32 v101, 16, v32
	v_and_b32_e32 v32, 0xffff0000, v32
	v_add_f32_e32 v101, 0, v101
	v_lshlrev_b32_e32 v106, 16, v33
	v_add_f32_e32 v32, v101, v32
	v_and_b32_e32 v33, 0xffff0000, v33
	v_add_f32_e32 v32, v32, v106
	v_lshlrev_b32_e32 v107, 16, v34
	v_add_f32_e32 v32, v32, v33
	v_and_b32_e32 v34, 0xffff0000, v34
	v_add_f32_e32 v32, v32, v107
	v_lshlrev_b32_e32 v125, 16, v35
	v_add_f32_e32 v32, v32, v34
	v_and_b32_e32 v35, 0xffff0000, v35
	v_add_f32_e32 v32, v32, v125
	v_add_f32_e32 v32, v32, v35
	s_waitcnt lgkmcnt(2)
	v_lshlrev_b32_e32 v33, 16, v36
	v_and_b32_e32 v34, 0xffff0000, v36
	v_add_f32_e32 v32, v32, v33
	v_lshlrev_b32_e32 v35, 16, v37
	v_add_f32_e32 v32, v32, v34
	v_and_b32_e32 v36, 0xffff0000, v37
	v_add_f32_e32 v32, v32, v35
	v_lshlrev_b32_e32 v37, 16, v38
	v_add_f32_e32 v32, v32, v36
	v_and_b32_e32 v38, 0xffff0000, v38
	v_add_f32_e32 v32, v32, v37
	v_lshlrev_b32_e32 v101, 16, v39
	v_add_f32_e32 v32, v32, v38
	v_and_b32_e32 v39, 0xffff0000, v39
	v_add_f32_e32 v32, v32, v101
	v_add_f32_e32 v32, v32, v39
	s_waitcnt lgkmcnt(1)
	v_lshlrev_b32_e32 v33, 16, v102
	v_and_b32_e32 v34, 0xffff0000, v102
	v_add_f32_e32 v32, v32, v33
	v_lshlrev_b32_e32 v35, 16, v103
	v_add_f32_e32 v32, v32, v34
	v_and_b32_e32 v36, 0xffff0000, v103
	v_add_f32_e32 v32, v32, v35
	v_lshlrev_b32_e32 v37, 16, v104
	v_add_f32_e32 v32, v32, v36
	v_and_b32_e32 v38, 0xffff0000, v104
	v_add_f32_e32 v32, v32, v37
	v_lshlrev_b32_e32 v39, 16, v105
	v_add_f32_e32 v32, v32, v38
	v_and_b32_e32 v101, 0xffff0000, v105
	v_add_f32_e32 v32, v32, v39
	v_add_f32_e32 v32, v32, v101
	s_waitcnt lgkmcnt(0)
	v_lshlrev_b32_e32 v33, 16, v126
	v_and_b32_e32 v34, 0xffff0000, v126
	v_add_f32_e32 v32, v32, v33
	v_lshlrev_b32_e32 v35, 16, v127
	v_add_f32_e32 v32, v32, v34
	v_and_b32_e32 v36, 0xffff0000, v127
	v_add_f32_e32 v32, v32, v35
	v_lshlrev_b32_e32 v37, 16, v128
	v_add_f32_e32 v32, v32, v36
	v_add_f32_e32 v36, v32, v37
	ds_read_b128 v[32:35], v112 offset:64
	v_and_b32_e32 v38, 0xffff0000, v128
	v_lshlrev_b32_e32 v39, 16, v129
	v_add_f32_e32 v36, v36, v38
	v_and_b32_e32 v101, 0xffff0000, v129
	v_add_f32_e32 v36, v36, v39
	v_add_f32_e32 v101, v36, v101
	ds_read_b128 v[36:39], v112 offset:80
	s_waitcnt lgkmcnt(1)
	v_lshlrev_b32_e32 v102, 16, v32
	v_and_b32_e32 v32, 0xffff0000, v32
	v_add_f32_e32 v101, v101, v102
	v_lshlrev_b32_e32 v103, 16, v33
	v_add_f32_e32 v32, v101, v32
	v_and_b32_e32 v33, 0xffff0000, v33
	v_add_f32_e32 v32, v32, v103
	v_lshlrev_b32_e32 v104, 16, v34
	v_add_f32_e32 v32, v32, v33
	v_and_b32_e32 v34, 0xffff0000, v34
	v_add_f32_e32 v32, v32, v104
	v_lshlrev_b32_e32 v105, 16, v35
	v_add_f32_e32 v32, v32, v34
	v_and_b32_e32 v35, 0xffff0000, v35
	v_add_f32_e32 v32, v32, v105
	v_add_f32_e32 v32, v32, v35
	s_waitcnt lgkmcnt(0)
	v_lshlrev_b32_e32 v33, 16, v36
	v_and_b32_e32 v34, 0xffff0000, v36
	v_add_f32_e32 v32, v32, v33
	v_lshlrev_b32_e32 v35, 16, v37
	v_add_f32_e32 v32, v32, v34
	v_and_b32_e32 v36, 0xffff0000, v37
	v_add_f32_e32 v32, v32, v35
	v_lshlrev_b32_e32 v37, 16, v38
	v_add_f32_e32 v32, v32, v36
	v_add_f32_e32 v36, v32, v37
	ds_read_b128 v[32:35], v112 offset:96
	v_and_b32_e32 v38, 0xffff0000, v38
	v_lshlrev_b32_e32 v101, 16, v39
	v_add_f32_e32 v36, v36, v38
	v_and_b32_e32 v39, 0xffff0000, v39
	v_add_f32_e32 v36, v36, v101
	v_add_f32_e32 v101, v36, v39
	ds_read_b128 v[36:39], v112 offset:112
	s_waitcnt lgkmcnt(1)
	v_lshlrev_b32_e32 v102, 16, v32
	v_and_b32_e32 v32, 0xffff0000, v32
	v_add_f32_e32 v101, v101, v102
	v_lshlrev_b32_e32 v103, 16, v33
	v_add_f32_e32 v32, v101, v32
	v_and_b32_e32 v33, 0xffff0000, v33
	v_add_f32_e32 v32, v32, v103
	v_lshlrev_b32_e32 v104, 16, v34
	v_add_f32_e32 v32, v32, v33
	v_and_b32_e32 v34, 0xffff0000, v34
	v_add_f32_e32 v32, v32, v104
	v_lshlrev_b32_e32 v105, 16, v35
	v_add_f32_e32 v32, v32, v34
	v_and_b32_e32 v35, 0xffff0000, v35
	v_add_f32_e32 v32, v32, v105
	v_add_f32_e32 v32, v32, v35
	s_waitcnt lgkmcnt(0)
	v_lshlrev_b32_e32 v33, 16, v36
	v_and_b32_e32 v34, 0xffff0000, v36
	v_add_f32_e32 v32, v32, v33
	v_lshlrev_b32_e32 v35, 16, v37
	v_add_f32_e32 v32, v32, v34
	v_and_b32_e32 v36, 0xffff0000, v37
	v_add_f32_e32 v32, v32, v35
	v_lshlrev_b32_e32 v37, 16, v38
	v_add_f32_e32 v32, v32, v36
	v_add_f32_e32 v36, v32, v37
	ds_read_b128 v[32:35], v112 offset:128
	v_and_b32_e32 v38, 0xffff0000, v38
	v_lshlrev_b32_e32 v101, 16, v39
	v_add_f32_e32 v36, v36, v38
	v_and_b32_e32 v39, 0xffff0000, v39
	v_add_f32_e32 v36, v36, v101
	v_add_f32_e32 v101, v36, v39
	ds_read_b128 v[36:39], v112 offset:144
	s_waitcnt lgkmcnt(1)
; __device__ __forceinline__ float frcp(float x) { return __builtin_amdgcn_rcpf(x); }
; __device__ void ml_out_tile(unsigned char* lds, const Params& p, int l, int b, int h, int n) {
;     ...
;     if (tid < 128) {
;       float rs = 0.f;
; #pragma unroll
;       for (int c8 = 0; c8 < 16; ++c8) {
;         float f[8];
;         unpack8(*(const uint4*)(Ps + tid * 136 + c8 * 8), f);
; #pragma unroll
;         for (int e = 0; e < 8; ++e) rs += f[e];
;       }
;       const float den = rs + WI[tid] * QN[tid];
;       DINV[tid] = frcp(fmaxf(fabsf(den), EM[tid]));
;     }
	v_lshlrev_b32_e32 v102, 16, v32
	v_and_b32_e32 v32, 0xffff0000, v32
	v_add_f32_e32 v101, v101, v102
	v_lshlrev_b32_e32 v103, 16, v33
	v_add_f32_e32 v32, v101, v32
	v_and_b32_e32 v33, 0xffff0000, v33
	v_add_f32_e32 v32, v32, v103
	v_lshlrev_b32_e32 v104, 16, v34
	v_add_f32_e32 v32, v32, v33
	v_and_b32_e32 v34, 0xffff0000, v34
	v_add_f32_e32 v32, v32, v104
	v_lshlrev_b32_e32 v105, 16, v35
	v_add_f32_e32 v32, v32, v34
	v_and_b32_e32 v35, 0xffff0000, v35
	v_add_f32_e32 v32, v32, v105
	v_add_f32_e32 v32, v32, v35
	s_waitcnt lgkmcnt(0)
	v_lshlrev_b32_e32 v33, 16, v36
	v_and_b32_e32 v34, 0xffff0000, v36
	v_add_f32_e32 v32, v32, v33
	v_lshlrev_b32_e32 v35, 16, v37
	v_add_f32_e32 v32, v32, v34
	v_and_b32_e32 v36, 0xffff0000, v37
	v_add_f32_e32 v32, v32, v35
	v_lshlrev_b32_e32 v37, 16, v38
	v_add_f32_e32 v32, v32, v36
	v_add_f32_e32 v36, v32, v37
	ds_read_b128 v[32:35], v112 offset:160
	v_and_b32_e32 v38, 0xffff0000, v38
	v_lshlrev_b32_e32 v101, 16, v39
	v_add_f32_e32 v36, v36, v38
	v_and_b32_e32 v39, 0xffff0000, v39
	v_add_f32_e32 v36, v36, v101
	v_add_f32_e32 v101, v36, v39
	ds_read_b128 v[36:39], v112 offset:176
	s_waitcnt lgkmcnt(1)
	v_lshlrev_b32_e32 v102, 16, v32
	v_and_b32_e32 v32, 0xffff0000, v32
	v_add_f32_e32 v101, v101, v102
	v_lshlrev_b32_e32 v103, 16, v33
	v_add_f32_e32 v32, v101, v32
	v_and_b32_e32 v33, 0xffff0000, v33
	v_add_f32_e32 v32, v32, v103
	v_lshlrev_b32_e32 v104, 16, v34
	v_add_f32_e32 v32, v32, v33
	v_and_b32_e32 v34, 0xffff0000, v34
	v_add_f32_e32 v32, v32, v104
	v_lshlrev_b32_e32 v105, 16, v35
	v_add_f32_e32 v32, v32, v34
	v_and_b32_e32 v35, 0xffff0000, v35
	v_add_f32_e32 v32, v32, v105
	v_add_f32_e32 v32, v32, v35
	s_waitcnt lgkmcnt(0)
	v_lshlrev_b32_e32 v33, 16, v36
	v_and_b32_e32 v34, 0xffff0000, v36
	v_add_f32_e32 v32, v32, v33
	v_lshlrev_b32_e32 v35, 16, v37
	v_add_f32_e32 v32, v32, v34
	v_and_b32_e32 v36, 0xffff0000, v37
	v_add_f32_e32 v32, v32, v35
	v_lshlrev_b32_e32 v37, 16, v38
	v_add_f32_e32 v32, v32, v36
	v_add_f32_e32 v36, v32, v37
	ds_read_b128 v[32:35], v112 offset:192
	v_and_b32_e32 v38, 0xffff0000, v38
	v_lshlrev_b32_e32 v101, 16, v39
	v_add_f32_e32 v36, v36, v38
	v_and_b32_e32 v39, 0xffff0000, v39
	v_add_f32_e32 v36, v36, v101
	v_add_f32_e32 v101, v36, v39
	ds_read_b128 v[36:39], v112 offset:208
	s_waitcnt lgkmcnt(1)
	v_lshlrev_b32_e32 v102, 16, v32
	v_and_b32_e32 v32, 0xffff0000, v32
	v_add_f32_e32 v101, v101, v102
	v_lshlrev_b32_e32 v103, 16, v33
	v_add_f32_e32 v32, v101, v32
	v_and_b32_e32 v33, 0xffff0000, v33
	v_add_f32_e32 v32, v32, v103
	v_lshlrev_b32_e32 v104, 16, v34
	v_add_f32_e32 v32, v32, v33
	v_and_b32_e32 v34, 0xffff0000, v34
	v_add_f32_e32 v32, v32, v104
	v_lshlrev_b32_e32 v105, 16, v35
	v_add_f32_e32 v32, v32, v34
	v_and_b32_e32 v35, 0xffff0000, v35
	v_add_f32_e32 v32, v32, v105
	v_add_f32_e32 v32, v32, v35
	s_waitcnt lgkmcnt(0)
	v_lshlrev_b32_e32 v33, 16, v36
	v_and_b32_e32 v34, 0xffff0000, v36
	v_add_f32_e32 v32, v32, v33
	v_lshlrev_b32_e32 v35, 16, v37
	v_add_f32_e32 v32, v32, v34
	v_and_b32_e32 v36, 0xffff0000, v37
	v_add_f32_e32 v32, v32, v35
	v_lshlrev_b32_e32 v37, 16, v38
	v_add_f32_e32 v32, v32, v36
	v_add_f32_e32 v36, v32, v37
	ds_read_b128 v[32:35], v112 offset:224
	v_and_b32_e32 v38, 0xffff0000, v38
	v_lshlrev_b32_e32 v101, 16, v39
	v_add_f32_e32 v36, v36, v38
	v_and_b32_e32 v39, 0xffff0000, v39
	v_add_f32_e32 v36, v36, v101
	v_add_f32_e32 v101, v36, v39
	ds_read_b128 v[36:39], v112 offset:240
	s_waitcnt lgkmcnt(1)
	v_lshlrev_b32_e32 v102, 16, v32
	v_and_b32_e32 v32, 0xffff0000, v32
	v_add_f32_e32 v101, v101, v102
	v_lshlrev_b32_e32 v103, 16, v33
	v_add_f32_e32 v32, v101, v32
	v_and_b32_e32 v33, 0xffff0000, v33
	v_add_f32_e32 v32, v32, v103
	v_lshlrev_b32_e32 v104, 16, v34
	v_add_f32_e32 v32, v32, v33
	v_and_b32_e32 v34, 0xffff0000, v34
	v_add_f32_e32 v32, v32, v104
	v_lshlrev_b32_e32 v105, 16, v35
	v_add_f32_e32 v32, v32, v34
	v_and_b32_e32 v35, 0xffff0000, v35
	v_add_f32_e32 v32, v32, v105
	v_add_f32_e32 v32, v32, v35
	s_waitcnt lgkmcnt(0)
	v_lshlrev_b32_e32 v33, 16, v36
	v_and_b32_e32 v34, 0xffff0000, v36
	v_add_f32_e32 v32, v32, v33
	v_lshlrev_b32_e32 v35, 16, v37
	v_add_f32_e32 v32, v32, v34
	v_and_b32_e32 v36, 0xffff0000, v37
	v_add_f32_e32 v32, v32, v35
	v_add_f32_e32 v34, v32, v36
	v_lshl_add_u32 v32, v197, 2, s76
	v_lshl_add_u32 v35, s33, 9, v123
	v_lshlrev_b32_e32 v37, 16, v38
	ds_read2st64_b32 v[32:33], v32 offset0:16 offset1:18
	ds_read_b32 v35, v35 offset:8704
	v_and_b32_e32 v38, 0xffff0000, v38
	v_add_f32_e32 v34, v34, v37
	v_lshlrev_b32_e32 v101, 16, v39
	v_add_f32_e32 v34, v34, v38
	v_and_b32_e32 v39, 0xffff0000, v39
	v_add_f32_e32 v34, v34, v101
	v_add_f32_e32 v34, v34, v39
	s_waitcnt lgkmcnt(0)
	v_fmac_f32_e32 v34, v32, v35
	v_max_f32_e32 v32, v33, v33
	v_max_f32_e64 v32, |v34|, v32
	v_rcp_f32_e32 v32, v32
	ds_write_b32 v113, v32
